# one static s_setprio 1 for waves 4-7 at kernel entry
# speedup vs baseline: 1.0006x; 1.0006x over previous
_Z10fwd_kernel6Params:
	v_cmp_lt_u32_e32 vcc, 0xff, v0
	s_cbranch_vccz .Lprio_skip
	s_setprio 1
.Lprio_skip:
	s_load_dwordx4 s[48:51], s[0:1], 0xc0
	s_load_dwordx2 s[84:85], s[0:1], 0xd0
	v_and_b32_e32 v142, 0x3ff, v0
	v_writelane_b32 v217, s2, 0
	s_add_u32 s2, s0, 0xd0
	s_addc_u32 s3, s1, 0
	v_writelane_b32 v217, s2, 1
	v_cmp_eq_u32_e64 s[4:5], 0, v142
	s_nop 0
	v_writelane_b32 v217, s3, 2
	s_mov_b64 s[2:3], exec
	v_writelane_b32 v217, s4, 3
	s_nop 1
	v_writelane_b32 v217, s5, 4
	s_and_b64 s[4:5], s[2:3], s[4:5]
	s_mov_b64 exec, s[4:5]
	s_cbranch_execz .LBB0_2
	s_add_i32 s4, 0, 0x24200
	v_mov_b32_e32 v1, 0
	v_mov_b32_e32 v2, s4
	s_add_i32 s4, 0, 0x24204
	ds_write_b32 v2, v1
	v_mov_b32_e32 v2, s4
	s_add_i32 s4, 0, 0x24208
	ds_write_b32 v2, v1
	v_mov_b32_e32 v2, s4
	s_add_i32 s4, 0, 0x2420c
	ds_write_b32 v2, v1
	v_mov_b32_e32 v2, s4
	ds_write_b32 v2, v1
